# grid-barrier spin loops poll without s_sleep (33 sites)
# speedup vs baseline: 1.0088x; 1.0088x over previous
; __device__ __forceinline__ unsigned xb_ld(unsigned* p)              { return __hip_atomic_load(p, __ATOMIC_RELAXED, __HIP_MEMORY_SCOPE_AGENT); }
; __device__ __forceinline__ void xcd_barrier_complete(unsigned* bar, unsigned x, unsigned& nloc, unsigned& nx) {
;     const unsigned G = gridDim.x * gridDim.y * gridDim.z;
;     unsigned sum, cnt, mine, sp = 0u;
;     for (;;) {
;         sum = 0u; cnt = 0u; mine = 0u;
; #pragma unroll
;         for (unsigned j = 0; j < 16; ++j) { const unsigned c = xb_ld(&bar[XB_XCNT(j)]); sum += c; cnt += (c > 0u) ? 1u : 0u; mine = (j == x) ? c : mine; }
;         if (sum == G) break;
;         __builtin_amdgcn_s_sleep(1);
;         if ((++sp & 255u) == 0u) { if (xb_ld(&bar[XB_TMO])) break; if (sp > XB_SPIN_CAP) { atomicAdd(&bar[XB_TMO], 1u); break; } }
;     }
.LBB0_250:
	global_load_dword v15, v16, s[6:7] sc1
	global_load_dword v0, v16, s[8:9] sc1
	global_load_dword v1, v16, s[10:11] sc1
	global_load_dword v2, v16, s[12:13] sc1
	global_load_dword v3, v16, s[14:15] sc1
	global_load_dword v4, v16, s[16:17] sc1
	global_load_dword v5, v16, s[18:19] sc1
	global_load_dword v6, v16, s[20:21] sc1
	global_load_dword v7, v16, s[22:23] sc1
	global_load_dword v8, v16, s[24:25] sc1
	global_load_dword v9, v16, s[26:27] sc1
	global_load_dword v10, v16, s[28:29] sc1
	global_load_dword v11, v16, s[30:31] sc1
	global_load_dword v12, v16, s[34:35] sc1
	global_load_dword v13, v16, s[36:37] sc1
	global_load_dword v14, v16, s[38:39] sc1
	s_mov_b64 s[40:41], -1
	s_mov_b64 s[42:43], -1
	s_waitcnt vmcnt(14)
	v_add_u32_e32 v17, v0, v15
	s_waitcnt vmcnt(13)
	v_add_u32_e32 v17, v17, v1
	s_waitcnt vmcnt(12)
	v_add_u32_e32 v17, v17, v2
	s_waitcnt vmcnt(11)
	v_add_u32_e32 v17, v17, v3
	s_waitcnt vmcnt(10)
	v_add_u32_e32 v17, v17, v4
	s_waitcnt vmcnt(9)
	v_add_u32_e32 v17, v17, v5
	s_waitcnt vmcnt(8)
	v_add_u32_e32 v17, v17, v6
	s_waitcnt vmcnt(7)
	v_add_u32_e32 v17, v17, v7
	s_waitcnt vmcnt(6)
	v_add_u32_e32 v17, v17, v8
	s_waitcnt vmcnt(5)
	v_add_u32_e32 v17, v17, v9
	s_waitcnt vmcnt(4)
	v_add_u32_e32 v17, v17, v10
	s_waitcnt vmcnt(3)
	v_add_u32_e32 v17, v17, v11
	s_waitcnt vmcnt(2)
	v_add_u32_e32 v17, v17, v12
	s_waitcnt vmcnt(1)
	v_add_u32_e32 v17, v17, v13
	s_waitcnt vmcnt(0)
	v_add_u32_e32 v17, v17, v14
	v_cmp_eq_u32_e32 vcc, s46, v17
	s_cbranch_vccnz .LBB0_249
	s_and_b32 s40, s47, 0xff
	s_cmp_eq_u32 s40, 0
	s_mov_b64 s[40:41], -1
	s_mov_b64 s[44:45], -1
	s_cbranch_scc1 .LBB0_254
	s_and_b64 vcc, exec, s[44:45]
	s_cbranch_vccz .LBB0_249

; __device__ __forceinline__ unsigned xb_ld(unsigned* p)              { return __hip_atomic_load(p, __ATOMIC_RELAXED, __HIP_MEMORY_SCOPE_AGENT); }
; __device__ __forceinline__ unsigned xb_add(unsigned* p, unsigned v) { return __hip_atomic_fetch_add(p, v, __ATOMIC_RELAXED, __HIP_MEMORY_SCOPE_AGENT); }
; #define XB_SPIN(cond, bar) do { unsigned _sp = 0; while (cond) { __builtin_amdgcn_s_sleep(1); \
;     if ((++_sp & 255u) == 0u) { if (xb_ld(&(bar)[XB_TMO])) break; if (_sp > XB_SPIN_CAP) { atomicAdd(&(bar)[XB_TMO], 1u); break; } } } } while (0)
; __device__ __forceinline__ void xcd_barrier(const XcdBarrier& b) {
;     ...
;             else XB_SPIN(xb_ld(&bar[XB_TOPGEN]) == tg, bar);
;             __builtin_amdgcn_fence(__ATOMIC_ACQUIRE, "agent");
;             xb_add(&bar[XB_XGEN(b.x)], 1u);
;             asm volatile("s_waitcnt vmcnt(0)" ::: "memory");
;         } else {
;             XB_SPIN(xb_ld(&bar[XB_XGEN(b.x)]) == gen, bar);
.LBB0_266:
	s_and_b32 s20, s24, 0xff
	s_mov_b64 s[18:19], -1
	s_cmp_lg_u32 s20, 0
	s_mov_b64 s[22:23], -1
	s_cbranch_scc0 .LBB0_269
	s_and_b64 vcc, exec, s[22:23]
	s_cbranch_vccz .LBB0_265

; __device__ __forceinline__ unsigned xb_ld(unsigned* p)              { return __hip_atomic_load(p, __ATOMIC_RELAXED, __HIP_MEMORY_SCOPE_AGENT); }
; __device__ __forceinline__ unsigned xb_add(unsigned* p, unsigned v) { return __hip_atomic_fetch_add(p, v, __ATOMIC_RELAXED, __HIP_MEMORY_SCOPE_AGENT); }
; #define XB_SPIN(cond, bar) do { unsigned _sp = 0; while (cond) { __builtin_amdgcn_s_sleep(1); \
;     if ((++_sp & 255u) == 0u) { if (xb_ld(&(bar)[XB_TMO])) break; if (_sp > XB_SPIN_CAP) { atomicAdd(&(bar)[XB_TMO], 1u); break; } } } } while (0)
; __device__ __forceinline__ void xcd_barrier(const XcdBarrier& b) {
;     ...
;             else XB_SPIN(xb_ld(&bar[XB_TOPGEN]) == tg, bar);
;             __builtin_amdgcn_fence(__ATOMIC_ACQUIRE, "agent");
;             xb_add(&bar[XB_XGEN(b.x)], 1u);
;             asm volatile("s_waitcnt vmcnt(0)" ::: "memory");
;         } else {
;             XB_SPIN(xb_ld(&bar[XB_XGEN(b.x)]) == gen, bar);
.LBB0_283:
	s_and_b32 s18, s24, 0xff
	s_cmp_lg_u32 s18, 0
	s_mov_b64 s[20:21], -1
	s_cbranch_scc0 .LBB0_286
	s_mov_b64 s[22:23], -1
	s_and_b64 vcc, exec, s[20:21]
	s_cbranch_vccz .LBB0_282

; __device__ __forceinline__ unsigned xb_ld(unsigned* p)              { return __hip_atomic_load(p, __ATOMIC_RELAXED, __HIP_MEMORY_SCOPE_AGENT); }
; __device__ __forceinline__ void xcd_barrier_complete(unsigned* bar, unsigned x, unsigned& nloc, unsigned& nx) {
;     const unsigned G = gridDim.x * gridDim.y * gridDim.z;
;     unsigned sum, cnt, mine, sp = 0u;
;     for (;;) {
;         sum = 0u; cnt = 0u; mine = 0u;
; #pragma unroll
;         for (unsigned j = 0; j < 16; ++j) { const unsigned c = xb_ld(&bar[XB_XCNT(j)]); sum += c; cnt += (c > 0u) ? 1u : 0u; mine = (j == x) ? c : mine; }
;         if (sum == G) break;
;         __builtin_amdgcn_s_sleep(1);
;         if ((++sp & 255u) == 0u) { if (xb_ld(&bar[XB_TMO])) break; if (sp > XB_SPIN_CAP) { atomicAdd(&bar[XB_TMO], 1u); break; } }
;     }
.LBB0_315:
	v_readlane_b32 s0, v252, 18
	v_readlane_b32 s1, v252, 19
	s_mov_b64 s[4:5], -1
	s_nop 3
	global_load_dword v0, v185, s[0:1] sc1
	v_readlane_b32 s0, v252, 20
	v_readlane_b32 s1, v252, 21
	s_nop 4
	global_load_dword v1, v185, s[0:1] sc1
	v_readlane_b32 s0, v252, 22
	v_readlane_b32 s1, v252, 23
	s_waitcnt vmcnt(0)
	v_add_u32_e32 v16, v1, v0
	s_nop 2
	global_load_dword v2, v185, s[0:1] sc1
	v_readlane_b32 s0, v252, 24
	v_readlane_b32 s1, v252, 25
	s_waitcnt vmcnt(0)
	v_add_u32_e32 v16, v16, v2
	s_nop 2
	global_load_dword v3, v185, s[0:1] sc1
	v_readlane_b32 s0, v252, 26
	v_readlane_b32 s1, v252, 27
	s_waitcnt vmcnt(0)
	v_add_u32_e32 v16, v16, v3
	s_nop 2
	global_load_dword v4, v185, s[0:1] sc1
	v_readlane_b32 s0, v252, 28
	v_readlane_b32 s1, v252, 29
	s_waitcnt vmcnt(0)
	v_add_u32_e32 v16, v16, v4
	s_nop 2
	global_load_dword v5, v185, s[0:1] sc1
	v_readlane_b32 s0, v252, 30
	v_readlane_b32 s1, v252, 31
	s_waitcnt vmcnt(0)
	v_add_u32_e32 v16, v16, v5
	s_nop 2
	global_load_dword v6, v185, s[0:1] sc1
	v_readlane_b32 s0, v252, 32
	v_readlane_b32 s1, v252, 33
	s_waitcnt vmcnt(0)
	v_add_u32_e32 v16, v16, v6
	s_nop 2
	global_load_dword v7, v185, s[0:1] sc1
	v_readlane_b32 s0, v252, 34
	v_readlane_b32 s1, v252, 35
	s_waitcnt vmcnt(0)
	v_add_u32_e32 v16, v16, v7
	s_nop 2
	global_load_dword v8, v185, s[0:1] sc1
	v_readlane_b32 s0, v252, 36
	v_readlane_b32 s1, v252, 37
	s_waitcnt vmcnt(0)
	v_add_u32_e32 v16, v16, v8
	s_nop 2
	global_load_dword v9, v185, s[0:1] sc1
	v_readlane_b32 s0, v252, 38
	v_readlane_b32 s1, v252, 39
	s_waitcnt vmcnt(0)
	v_add_u32_e32 v16, v16, v9
	s_nop 2
	global_load_dword v10, v185, s[0:1] sc1
	v_readlane_b32 s0, v252, 40
	v_readlane_b32 s1, v252, 41
	s_waitcnt vmcnt(0)
	v_add_u32_e32 v16, v16, v10
	s_nop 2
	global_load_dword v11, v185, s[0:1] sc1
	v_readlane_b32 s0, v252, 42
	v_readlane_b32 s1, v252, 43
	s_waitcnt vmcnt(0)
	v_add_u32_e32 v16, v16, v11
	s_nop 2
	global_load_dword v12, v185, s[0:1] sc1
	v_readlane_b32 s0, v252, 44
	v_readlane_b32 s1, v252, 45
	s_waitcnt vmcnt(0)
	v_add_u32_e32 v16, v16, v12
	s_nop 2
	global_load_dword v13, v185, s[0:1] sc1
	v_readlane_b32 s0, v252, 46
	v_readlane_b32 s1, v252, 47
	s_waitcnt vmcnt(0)
	v_add_u32_e32 v16, v16, v13
	s_nop 2
	global_load_dword v14, v185, s[0:1] sc1
	v_readlane_b32 s0, v252, 48
	v_readlane_b32 s1, v252, 49
	s_waitcnt vmcnt(0)
	v_add_u32_e32 v16, v16, v14
	s_nop 2
	global_load_dword v15, v185, s[0:1] sc1
	s_mov_b64 s[0:1], -1
	s_waitcnt vmcnt(0)
	v_add_u32_e32 v16, v16, v15
	v_cmp_eq_u32_e32 vcc, s8, v16
	s_cbranch_vccnz .LBB0_314
	s_and_b32 s0, s9, 0xff
	s_cmp_eq_u32 s0, 0
	s_mov_b64 s[0:1], -1
	s_mov_b64 s[6:7], -1
	s_cbranch_scc1 .LBB0_319
	s_and_b64 vcc, exec, s[6:7]
	s_cbranch_vccz .LBB0_314

; __device__ __forceinline__ unsigned xb_ld(unsigned* p)              { return __hip_atomic_load(p, __ATOMIC_RELAXED, __HIP_MEMORY_SCOPE_AGENT); }
; __device__ __forceinline__ unsigned xb_add(unsigned* p, unsigned v) { return __hip_atomic_fetch_add(p, v, __ATOMIC_RELAXED, __HIP_MEMORY_SCOPE_AGENT); }
; #define XB_SPIN(cond, bar) do { unsigned _sp = 0; while (cond) { __builtin_amdgcn_s_sleep(1); \
;     if ((++_sp & 255u) == 0u) { if (xb_ld(&(bar)[XB_TMO])) break; if (_sp > XB_SPIN_CAP) { atomicAdd(&(bar)[XB_TMO], 1u); break; } } } } while (0)
; __device__ __forceinline__ void xcd_barrier(const XcdBarrier& b) {
;     ...
;             else XB_SPIN(xb_ld(&bar[XB_TOPGEN]) == tg, bar);
;             __builtin_amdgcn_fence(__ATOMIC_ACQUIRE, "agent");
;             xb_add(&bar[XB_XGEN(b.x)], 1u);
;             asm volatile("s_waitcnt vmcnt(0)" ::: "memory");
;         } else {
;             XB_SPIN(xb_ld(&bar[XB_XGEN(b.x)]) == gen, bar);
.LBB0_331:
	s_and_b32 s12, s16, 0xff
	s_mov_b64 s[0:1], -1
	s_cmp_lg_u32 s12, 0
	s_mov_b64 s[14:15], -1
	s_cbranch_scc0 .LBB0_334
	s_and_b64 vcc, exec, s[14:15]
	s_cbranch_vccz .LBB0_330

; __device__ __forceinline__ unsigned xb_ld(unsigned* p)              { return __hip_atomic_load(p, __ATOMIC_RELAXED, __HIP_MEMORY_SCOPE_AGENT); }
; __device__ __forceinline__ unsigned xb_add(unsigned* p, unsigned v) { return __hip_atomic_fetch_add(p, v, __ATOMIC_RELAXED, __HIP_MEMORY_SCOPE_AGENT); }
; #define XB_SPIN(cond, bar) do { unsigned _sp = 0; while (cond) { __builtin_amdgcn_s_sleep(1); \
;     if ((++_sp & 255u) == 0u) { if (xb_ld(&(bar)[XB_TMO])) break; if (_sp > XB_SPIN_CAP) { atomicAdd(&(bar)[XB_TMO], 1u); break; } } } } while (0)
; __device__ __forceinline__ void xcd_barrier(const XcdBarrier& b) {
;     ...
;             else XB_SPIN(xb_ld(&bar[XB_TOPGEN]) == tg, bar);
;             __builtin_amdgcn_fence(__ATOMIC_ACQUIRE, "agent");
;             xb_add(&bar[XB_XGEN(b.x)], 1u);
;             asm volatile("s_waitcnt vmcnt(0)" ::: "memory");
;         } else {
;             XB_SPIN(xb_ld(&bar[XB_XGEN(b.x)]) == gen, bar);
.LBB0_512:
	s_and_b32 s12, s17, 0xff
	s_mov_b64 s[0:1], -1
	s_cmp_lg_u32 s12, 0
	s_mov_b64 s[14:15], -1
	s_cbranch_scc0 .LBB0_515
	s_and_b64 vcc, exec, s[14:15]
	s_cbranch_vccz .LBB0_511
